# in1 (phase 9) tile order rebalanced across XCDs: every XCD gets the same mix of rope/transposed-copy tiles and plain tiles
# speedup vs baseline: 1.0113x; 1.0075x over previous
; DI int sched_tile(const Sched& sc, int round, int MT, int NT, int& mt, int& nt) {
;   const int total = MT * NT;
;   const int per = (total + sc.nx - 1) / sc.nx;
;   const int off = round * sc.minloc;
;   if (off >= per) return 2;
;   if (sc.rank >= sc.minloc) return 1;
;   int L = off + sc.rank;
;   if (L >= per) return 1;
;   L += sc.xs * per;
;   if (L >= total) return 1;
;   for (int c0 = 0; c0 < NT; c0 += 8) {
;     const int w = NT - c0 < 8 ? NT - c0 : 8;
;     const int cnt = MT * w;
;     if (L < cnt) { mt = L / w; nt = c0 + L - mt * w; return 0; }
; DI void phase_in1_256(const Sched& sc, const Params& p, char* smem) {
;     ...
;   for (int round = 0;; ++round) {
;     int mt = 0, nt = 0;
;     const int st = sched_tile(sc, round, 128, 14, mt, nt);
;     if (st == 2) break;
;     if (st == 1) continue;
.LBB0_756:
	s_mul_i32 s4, s42, s90
	s_cmp_ge_i32 s4, s33
	s_cselect_b64 s[6:7], -1, 0
	s_and_b64 s[20:21], s[6:7], exec
	s_cselect_b32 s5, 2, 1
	s_or_b64 s[6:7], s[6:7], s[94:95]
	s_and_b64 vcc, exec, s[6:7]
	v_mov_b32_e32 v0, s5
	s_mov_b32 s52, 0
	s_mov_b32 s20, 0
	s_cbranch_vccnz .LBB0_764
	s_add_i32 s4, s4, s92
	s_cmp_ge_i32 s4, s33
	s_cbranch_scc1 .LBB0_762
	s_add_i32 s22, s41, s4
	s_cmp_lg_u32 s33, 0xe0
	s_cbranch_scc1 .Lin1_noremap
	s_lshr_b32 s22, s41, 5
	s_mul_i32 s22, s22, 37
	s_lshr_b32 s22, s22, 8
	s_cmp_lt_u32 s4, 0x80
	s_cbranch_scc0 .Lin1_g2
	s_lshl_b32 s22, s22, 7
	s_add_i32 s22, s22, s4
	s_branch .Lin1_noremap
.Lin1_g2:
	s_mul_i32 s22, s22, 0x60
	s_add_i32 s22, s22, s4
	s_addk_i32 s22, 0x380
.Lin1_noremap:
	s_cmpk_gt_i32 s22, 0x6ff
	s_cbranch_scc1 .LBB0_763
	s_cmpk_gt_i32 s22, 0x3ff
	s_cselect_b64 s[4:5], -1, 0
	s_mov_b64 s[6:7], -1
	s_and_b64 vcc, exec, s[4:5]
	s_cbranch_vccnz .LBB0_804
	s_ashr_i32 s6, s22, 31
	s_lshr_b32 s6, s6, 29
	s_add_i32 s6, s22, s6
	s_ashr_i32 s21, s6, 3
	s_and_b32 s6, s6, -8
	s_sub_i32 s20, s22, s6
	s_cbranch_execz .LBB0_805
